# no-op max/add0 removal extended to all attention step copies; hoist loop-invariant wsf address
# speedup vs baseline: 1.0245x; 1.0011x over previous
.LBB0_379:
	s_and_b32 s22, s25, 0x3fffffc0
	s_lshl_b32 s22, s22, 2
	v_lshlrev_b32_e32 v0, 10, v201
	v_lshlrev_b32_e32 v2, 4, v200
	s_add_i32 s31, s22, 0
	v_add3_u32 v208, 0, v0, v2
	v_mov_b32_e32 v2, v1
	v_mov_b32_e32 v3, v1
	v_mov_b32_e32 v4, v1
	v_mov_b32_e32 v5, v1
	v_mov_b32_e32 v6, v1
	v_mov_b32_e32 v7, v1
	v_mov_b32_e32 v8, v1
	v_mov_b32_e32 v9, v1
	v_mov_b32_e32 v10, v1
	v_mov_b32_e32 v11, v1
	v_mov_b32_e32 v12, v1
	v_mov_b32_e32 v13, v1
	v_mov_b32_e32 v14, v1
	v_mov_b32_e32 v15, v1
	s_cmp_lg_u32 0, -1
	v_mov_b32_e32 v0, v1
	v_mov_b64_e32 v[16:17], v[14:15]
	s_cselect_b32 s22, 0, 0
	v_mov_b64_e32 v[14:15], v[12:13]
	v_mov_b64_e32 v[12:13], v[10:11]
	v_mov_b64_e32 v[10:11], v[8:9]
	v_mov_b64_e32 v[8:9], v[6:7]
	v_mov_b64_e32 v[6:7], v[4:5]
	v_mov_b64_e32 v[4:5], v[2:3]
	v_mov_b64_e32 v[2:3], v[0:1]
	s_add_i32 s12, s22, s12
	v_lshl_add_u64 v[26:27], v[82:83], 0, s[62:63]
	s_add_i32 s22, s12, 0x4000
	s_mov_b32 s23, m0
	s_mov_b32 m0, s22
	s_nop 0
	global_load_lds_dwordx4 v[26:27], off
	s_mov_b32 m0, s23
	s_waitcnt vmcnt(3) lgkmcnt(0)
	s_barrier
	ds_read_b128 v[66:69], v208
	ds_read_b128 v[70:73], v208 offset:512
	v_pk_mul_f32 v[24:25], v[24:25], s[60:61] op_sel_hi:[1,0]
	v_pk_mul_f32 v[22:23], v[22:23], s[60:61] op_sel_hi:[1,0]
	v_pk_mul_f32 v[20:21], v[20:21], s[60:61] op_sel_hi:[1,0]
	v_pk_mul_f32 v[18:19], v[18:19], s[60:61] op_sel_hi:[1,0]
	v_cvt_pk_bf16_f32 v142, v24, v25
	v_cvt_pk_bf16_f32 v143, v22, v23
	v_cvt_pk_bf16_f32 v144, v20, v21
	v_cvt_pk_bf16_f32 v145, v18, v19
	v_pk_mul_f32 v[44:45], v[44:45], s[60:61] op_sel_hi:[1,0]
	v_pk_mul_f32 v[42:43], v[42:43], s[60:61] op_sel_hi:[1,0]
	s_waitcnt lgkmcnt(1)
	v_mfma_f32_32x32x16_bf16 v[18:33], v[66:69], v[142:145], v[2:17]
	ds_read_b128 v[66:69], v208 offset:2048
	v_cvt_pk_bf16_f32 v136, v44, v45
	v_cvt_pk_bf16_f32 v137, v42, v43
	ds_read_b128 v[42:45], v208 offset:2560
	v_mul_f32_e64 v48, v48, s60
	v_mul_f32_e64 v49, v49, s60
	v_pk_mul_f32 v[46:47], v[46:47], s[60:61] op_sel_hi:[1,0]
	v_cvt_pk_bf16_f32 v134, v48, v49
	s_waitcnt lgkmcnt(2)
	v_mfma_f32_32x32x16_bf16 v[2:17], v[70:73], v[142:145], v[2:17]
	v_cvt_pk_bf16_f32 v135, v46, v47
	v_mov_b32_e32 v63, v53
	v_mov_b32_e32 v61, v55
	v_mov_b32_e32 v59, v57
	ds_read_b128 v[46:49], v208 offset:4096
	v_mov_b32_e32 v65, v51
	v_pk_mul_f32 v[50:51], v[64:65], s[60:61] op_sel_hi:[1,0]
	s_waitcnt lgkmcnt(1)
	v_mfma_f32_32x32x16_bf16 v[2:17], v[42:45], v[134:137], v[2:17]
	v_mul_f32_e64 v42, v62, s60
	v_mul_f32_e64 v43, v63, s60
	v_cvt_pk_bf16_f32 v126, v50, v51
	v_cvt_pk_bf16_f32 v127, v42, v43
	v_mul_f32_e64 v42, v60, s60
	v_mul_f32_e64 v43, v61, s60
	v_pk_mul_f32 v[34:35], v[34:35], s[60:61] op_sel_hi:[1,0]
	v_cvt_pk_bf16_f32 v128, v42, v43
	v_pk_mul_f32 v[42:43], v[58:59], s[60:61] op_sel_hi:[1,0]
	v_mfma_f32_32x32x16_bf16 v[18:33], v[66:69], v[134:137], v[18:33]
	v_cvt_pk_bf16_f32 v129, v42, v43
	ds_read_b128 v[42:45], v208 offset:4608
	v_lshlrev_b32_e32 v0, 1, v86
	v_cvt_pk_bf16_f32 v119, v34, v35
	v_mul_f32_e64 v34, v36, s60
	v_mul_f32_e64 v35, v37, s60
	v_and_b32_e32 v205, 32, v0
	v_pk_mul_f32 v[38:39], v[38:39], s[60:61] op_sel_hi:[1,0]
	s_waitcnt lgkmcnt(1)
	v_mfma_f32_32x32x16_bf16 v[18:33], v[46:49], v[126:129], v[18:33]
	ds_read_b128 v[46:49], v208 offset:6656
	ds_read_b128 v[50:53], v208 offset:6144
	v_cvt_pk_bf16_f32 v120, v34, v35
	v_mul_f32_e64 v34, v40, s60
	v_mul_f32_e64 v35, v41, s60
	v_lshlrev_b32_e32 v0, 4, v86
	v_cvt_pk_bf16_f32 v118, v38, v39
	v_cvt_pk_bf16_f32 v121, v34, v35
	v_and_b32_e32 v0, 0xc0, v0
	s_waitcnt lgkmcnt(2)
	v_mfma_f32_32x32x16_bf16 v[2:17], v[42:45], v[126:129], v[2:17]
	v_lshl_or_b32 v204, v201, 8, v0
	v_add_u32_e32 v0, 0, v205
	v_add3_u32 v209, v0, v202, v204
	s_mov_b64 s[38:39], 0x4000
	s_add_i32 s12, s12, 0x8000
	s_mov_b32 s22, 1
	s_mov_b32 s36, 0
	s_waitcnt lgkmcnt(0)
	v_mfma_f32_32x32x16_bf16 v[18:33], v[50:53], v[118:121], v[18:33]
	s_movk_i32 s37, 0x4000
	s_and_b64 vcc, exec, s[4:5]
	v_cmp_gt_u32_e64 s[4:5], 32, v198
	v_lshl_add_u32 v206, v200, 2, s31
	s_mul_hi_u32 s40, s20, 0x110000
	v_mfma_f32_32x32x16_bf16 v[2:17], v[46:49], v[118:121], v[2:17]
	s_nop 15
	s_nop 7
	s_nop 0
	v_max3_f32 v0, v18, v19, v2
	v_max3_f32 v34, v20, v21, v3
	s_nop 0
	v_max3_f32 v0, v0, v4, v5
	v_max3_f32 v34, v34, v24, v25
	s_nop 0
	v_max3_f32 v0, v0, v22, v23
	v_max3_f32 v34, v34, v8, v9
	s_nop 0
	v_max3_f32 v0, v0, v6, v7
	v_max3_f32 v34, v34, v28, v29
	s_nop 0
	v_max3_f32 v0, v0, v26, v27
	v_max3_f32 v34, v34, v12, v13
	s_nop 0
	v_max3_f32 v0, v0, v10, v11
	v_max3_f32 v34, v34, v32, v33
	s_nop 0
	v_max3_f32 v0, v0, v30, v31
	v_max3_f32 v34, v34, v16, v17
	s_nop 0
	v_max3_f32 v0, v0, v14, v15
	s_nop 0
	v_max_f32_e32 v0, v0, v34
	s_nop 0
	v_mov_b32_e32 v34, v0
	s_nop 1
	v_permlane32_swap_b32_e32 v0, v34
	v_max_f32_e32 v0, v0, v34
	s_nop 0
	v_add_f32_e32 v207, v1, v0
	v_sub_f32_e32 v2, v2, v0
	v_sub_f32_e32 v3, v3, v0
	v_sub_f32_e32 v18, v18, v0
	v_sub_f32_e32 v19, v19, v0
	v_sub_f32_e32 v20, v20, v0
	s_nop 0
	v_xor_b32_e32 v34, 0x80000000, v207
	v_mov_b32_e32 v35, v34
	v_mov_b32_e32 v36, v34
	v_mov_b32_e32 v37, v34
	v_mov_b32_e32 v38, v34
	v_mov_b32_e32 v39, v34
	v_mov_b32_e32 v40, v34
	v_mov_b32_e32 v41, v34
	v_mov_b32_e32 v42, v34
	v_mov_b32_e32 v43, v34
	v_mov_b32_e32 v44, v34
	v_mov_b32_e32 v45, v34
	v_mov_b32_e32 v46, v34
	v_mov_b32_e32 v47, v34
	v_mov_b32_e32 v48, v34
	v_mov_b32_e32 v49, v34
	s_waitcnt vmcnt(0) lgkmcnt(0)
	s_barrier
	v_exp_f32_e32 v50, v2
	v_exp_f32_e32 v51, v3
	v_lshl_add_u64 v[2:3], v[82:83], 0, s[64:65]
	s_mov_b32 s23, m0
	s_mov_b32 m0, s29
	s_nop 0
	global_load_lds_dwordx4 v[2:3], off
	s_mov_b32 m0, s23
	v_lshl_add_u64 v[2:3], v[84:85], 0, s[38:39]
	s_mov_b32 s23, m0
	s_mov_b32 m0, s12
	s_nop 0
	global_load_lds_dwordx4 v[2:3], off
	s_mov_b32 m0, s23
	ds_read_b128 v[174:177], v208 offset:8192
	ds_read_b128 v[170:173], v208 offset:8704
	ds_read_b128 v[166:169], v208 offset:10240
	ds_read_b128 v[162:165], v208 offset:10752
	ds_read_b128 v[158:161], v208 offset:12288
	ds_read_b128 v[154:157], v208 offset:12800
	ds_read_b128 v[150:153], v208 offset:14336
	ds_read_b128 v[146:149], v208 offset:14848
	v_sub_f32_e32 v4, v4, v0
	v_sub_f32_e32 v21, v21, v0
	v_sub_f32_e32 v5, v5, v0
	v_sub_f32_e32 v22, v22, v0
	v_sub_f32_e32 v6, v6, v0
	v_sub_f32_e32 v23, v23, v0
	v_sub_f32_e32 v7, v7, v0
	v_sub_f32_e32 v24, v24, v0
	v_sub_f32_e32 v8, v8, v0
	v_sub_f32_e32 v25, v25, v0
	v_sub_f32_e32 v9, v9, v0
	v_sub_f32_e32 v26, v26, v0
	v_sub_f32_e32 v10, v10, v0
	v_sub_f32_e32 v27, v27, v0
	v_sub_f32_e32 v11, v11, v0
	v_sub_f32_e32 v28, v28, v0
	v_sub_f32_e32 v12, v12, v0
	v_sub_f32_e32 v29, v29, v0
	v_sub_f32_e32 v13, v13, v0
	v_sub_f32_e32 v30, v30, v0
	v_sub_f32_e32 v14, v14, v0
	v_sub_f32_e32 v31, v31, v0
	v_sub_f32_e32 v15, v15, v0
	v_sub_f32_e32 v32, v32, v0
	v_sub_f32_e32 v16, v16, v0
	v_sub_f32_e32 v33, v33, v0
	v_sub_f32_e32 v0, v17, v0
	v_exp_f32_e32 v66, v18
	v_exp_f32_e32 v67, v19
	v_exp_f32_e32 v68, v20
	v_exp_f32_e32 v69, v21
	v_exp_f32_e32 v70, v22
	v_exp_f32_e32 v71, v23
	v_exp_f32_e32 v72, v24
	v_exp_f32_e32 v73, v25
	v_exp_f32_e32 v74, v26
	v_exp_f32_e32 v75, v27
	v_exp_f32_e32 v76, v28
	v_exp_f32_e32 v77, v29
	v_exp_f32_e32 v78, v30
	v_exp_f32_e32 v79, v31
	v_exp_f32_e32 v80, v32
	v_exp_f32_e32 v81, v33
	v_exp_f32_e32 v52, v4
	v_exp_f32_e32 v53, v5
	v_exp_f32_e32 v54, v6
	v_exp_f32_e32 v55, v7
	v_exp_f32_e32 v56, v8
	v_exp_f32_e32 v57, v9
	v_exp_f32_e32 v58, v10
	v_exp_f32_e32 v59, v11
	v_exp_f32_e32 v60, v12
	v_exp_f32_e32 v61, v13
	v_exp_f32_e32 v62, v14
	v_exp_f32_e32 v63, v15
	v_exp_f32_e32 v64, v16
	v_exp_f32_e32 v65, v0
	s_waitcnt vmcnt(2) lgkmcnt(0)
	s_barrier
	v_and_b32_e32 v0, 3, v86
	s_mul_i32 s39, s21, 0x110000
	s_mul_i32 s38, s20, 0x110000
	v_lshlrev_b32_e32 v0, 4, v0
	s_cbranch_vccnz .LBB0_395
	s_lshl_b32 s12, s24, 5
	s_and_b32 s12, s12, 0x80
	s_add_i32 s22, s40, s39
	s_lshl_b64 s[20:21], s[18:19], 1
	s_add_u32 s20, s20, s38
	s_addc_u32 s21, s21, s22
	v_lshl_add_u64 v[2:3], s[20:21], 0, v[0:1]
	s_lshl_b32 s20, s25, 6
	s_and_b32 s20, s20, 0x3000
	v_lshl_or_b32 v4, v192, 8, s20
	s_lshl_b64 s[20:21], s[6:7], 1
	s_add_u32 s20, s46, s20
	s_addc_u32 s21, s47, s21
	v_mov_b32_e32 v5, v1
	s_add_u32 s20, s20, s38
	v_lshl_add_u64 v[2:3], v[2:3], 0, v[4:5]
	v_mov_b32_e32 v183, v1
	s_addc_u32 s21, s21, s22
	v_mov_b32_e32 v194, 0
	s_mov_b32 s41, 6
	v_lshl_add_u64 v[184:185], s[46:47], 0, v[2:3]
	v_lshl_add_u64 v[186:187], s[20:21], 0, v[182:183]
	s_movk_i32 s36, 0x4000
	s_movk_i32 s72, 0x2000
	s_mov_b32 s20, 0
	v_mov_b32_e32 v18, 0
	v_mov_b32_e32 v19, v194
	v_mov_b32_e32 v20, v194
	v_mov_b32_e32 v21, v194
	v_mov_b32_e32 v22, v194
	v_mov_b32_e32 v23, v194
	v_mov_b32_e32 v24, v194
	v_mov_b32_e32 v25, v194
	v_mov_b32_e32 v26, v194
	v_mov_b32_e32 v27, v194
	v_mov_b32_e32 v28, v194
	v_mov_b32_e32 v29, v194
	v_mov_b32_e32 v30, v194
	v_mov_b32_e32 v31, v194
	v_mov_b32_e32 v32, v194
	v_mov_b32_e32 v33, v194
	v_mov_b32_e32 v2, v194
	v_mov_b32_e32 v3, v194
	v_mov_b32_e32 v4, v194
	v_mov_b32_e32 v5, v194
	v_mov_b32_e32 v6, v194
	v_mov_b32_e32 v7, v194
	v_mov_b32_e32 v8, v194
	v_mov_b32_e32 v9, v194
	v_mov_b32_e32 v10, v194
	v_mov_b32_e32 v11, v194
	v_mov_b32_e32 v12, v194
	v_mov_b32_e32 v13, v194
	v_mov_b32_e32 v14, v194
	v_mov_b32_e32 v15, v194
	v_mov_b32_e32 v16, v194
	v_mov_b32_e32 v17, v194
	v_add_u32_e32 v193, s31, v203
	v_readfirstlane_b32 s98, v186
	v_readfirstlane_b32 s99, v187
	v_readfirstlane_b32 s100, v184
	v_readfirstlane_b32 s101, v185
	s_nop 1
	v_subrev_u32_e32 v226, s98, v186
	v_subrev_u32_e32 v228, s100, v184
	v_add_u32_e32 v227, 0x4000, v226
	v_add_u32_e32 v229, 0x4000, v228
	s_nop 1
	s_add_u32 s98, s98, s12
	s_addc_u32 s99, s99, s13
	s_add_u32 s98, s98, s0
	s_addc_u32 s99, s99, s1
	s_add_u32 s100, s100, s12
	s_addc_u32 s101, s101, s13
	s_add_u32 s100, s100, s66
	s_addc_u32 s101, s101, s67

.LBB0_382:
	s_waitcnt lgkmcnt(14)
	v_mfma_f32_32x32x16_bf16 v[18:33], v[138:141], v[178:181], v[18:33]
	v_exp_f32_e32 v98, v98
	v_exp_f32_e32 v99, v99
	v_exp_f32_e32 v100, v100
	v_exp_f32_e32 v101, v101
	s_waitcnt lgkmcnt(12)
	v_mfma_f32_32x32x16_bf16 v[2:17], v[138:141], v[174:177], v[2:17]
	v_exp_f32_e32 v102, v102
	v_exp_f32_e32 v103, v103
	v_exp_f32_e32 v104, v104
	v_exp_f32_e32 v105, v105
	v_add_u32_e32 v78, s36, v208
	ds_read_b128 v[62:65], v78
	ds_read_b128 v[174:177], v78 offset:512
	s_waitcnt lgkmcnt(12)
	v_mfma_f32_32x32x16_bf16 v[18:33], v[130:133], v[66:69], v[18:33]
	v_exp_f32_e32 v106, v106
	v_exp_f32_e32 v107, v107
	v_exp_f32_e32 v108, v108
	v_exp_f32_e32 v109, v109
	ds_read_b128 v[178:181], v78 offset:2048
	ds_read_b128 v[170:173], v78 offset:2560
	s_waitcnt lgkmcnt(12)
	v_mfma_f32_32x32x16_bf16 v[2:17], v[130:133], v[70:73], v[2:17]
	v_exp_f32_e32 v110, v110
	v_exp_f32_e32 v111, v111
	v_exp_f32_e32 v112, v112
	v_exp_f32_e32 v113, v113
	ds_read_b128 v[166:169], v78 offset:4096
	ds_read_b128 v[162:165], v78 offset:4608
	s_waitcnt lgkmcnt(12)
	v_mfma_f32_32x32x16_bf16 v[18:33], v[122:125], v[74:77], v[18:33]
	v_exp_f32_e32 v82, v82
	v_exp_f32_e32 v83, v83
	v_exp_f32_e32 v84, v84
	v_exp_f32_e32 v85, v85
	ds_read_b128 v[158:161], v78 offset:6144
	ds_read_b128 v[154:157], v78 offset:6656
	s_waitcnt lgkmcnt(12)
	v_mfma_f32_32x32x16_bf16 v[2:17], v[122:125], v[50:53], v[2:17]
	v_exp_f32_e32 v86, v86
	v_exp_f32_e32 v87, v87
	v_exp_f32_e32 v88, v88
	v_exp_f32_e32 v89, v89
	s_waitcnt lgkmcnt(10)
	v_mfma_f32_32x32x16_bf16 v[18:33], v[114:117], v[54:57], v[18:33]
	v_exp_f32_e32 v90, v90
	v_exp_f32_e32 v91, v91
	v_exp_f32_e32 v92, v92
	v_exp_f32_e32 v93, v93
	s_waitcnt lgkmcnt(8)
	v_mfma_f32_32x32x16_bf16 v[2:17], v[114:117], v[58:61], v[2:17]
	v_exp_f32_e32 v94, v94
	v_exp_f32_e32 v95, v95
	v_exp_f32_e32 v96, v96
	v_exp_f32_e32 v97, v97
	s_waitcnt vmcnt(2) lgkmcnt(0)
	s_barrier
	s_andn2_b64 vcc, exec, s[20:21]
	s_cbranch_vccnz .LBB0_384
	s_waitcnt lgkmcnt(0)
	ds_read_b128 v[50:53], v193 offset:49248
	ds_read_b128 v[54:57], v193 offset:49216
	ds_read_b128 v[58:61], v193 offset:49184
	ds_read_b128 v[66:69], v193 offset:49152
	s_waitcnt lgkmcnt(3)
	v_pk_mul_f32 v[30:31], v[30:31], v[50:51]
	s_waitcnt lgkmcnt(2)
	v_pk_mul_f32 v[26:27], v[26:27], v[54:55]
	s_waitcnt lgkmcnt(1)
	v_pk_mul_f32 v[22:23], v[22:23], v[58:59]
	v_pk_mul_f32 v[32:33], v[32:33], v[52:53]
	v_pk_mul_f32 v[28:29], v[28:29], v[56:57]
	v_pk_mul_f32 v[24:25], v[24:25], v[60:61]
	s_waitcnt lgkmcnt(0)
	v_pk_mul_f32 v[20:21], v[20:21], v[68:69]
	v_pk_mul_f32 v[18:19], v[18:19], v[66:67]
	v_pk_mul_f32 v[14:15], v[14:15], v[50:51]
	v_pk_mul_f32 v[10:11], v[10:11], v[54:55]
	v_pk_mul_f32 v[6:7], v[6:7], v[58:59]
	v_pk_mul_f32 v[16:17], v[16:17], v[52:53]
	v_pk_mul_f32 v[12:13], v[12:13], v[56:57]
	v_pk_mul_f32 v[8:9], v[8:9], v[60:61]
	v_pk_mul_f32 v[4:5], v[4:5], v[68:69]
	v_pk_mul_f32 v[2:3], v[2:3], v[66:67]

.LBB0_397:
	v_add_u32_e32 v0, s37, v209
	ds_read_b64_tr_b16 v[98:99], v0 offset:24576
	ds_read_b64_tr_b16 v[100:101], v0 offset:25088
	v_add_f32_e32 v82, v66, v67
	v_add_f32_e32 v82, v68, v82
	v_add_f32_e32 v82, v69, v82
	v_add_f32_e32 v82, v70, v82
	v_add_f32_e32 v102, v71, v82
	s_waitcnt lgkmcnt(9)
	v_mfma_f32_32x32x16_bf16 v[82:97], v[174:177], v[142:145], v[34:49]
	v_cvt_pk_bf16_f32 v138, v66, v67
	v_cvt_pk_bf16_f32 v139, v68, v69
	ds_read_b64_tr_b16 v[66:67], v0 offset:28672
	ds_read_b64_tr_b16 v[68:69], v0 offset:29184
	s_waitcnt lgkmcnt(10)
	v_mfma_f32_32x32x16_bf16 v[34:49], v[170:173], v[142:145], v[34:49]
	v_add_f32_e32 v102, v72, v102
	v_add_f32_e32 v102, v73, v102
	v_add_f32_e32 v102, v74, v102
	v_add_f32_e32 v102, v75, v102
	v_cvt_pk_bf16_f32 v140, v70, v71
	v_cvt_pk_bf16_f32 v141, v72, v73
	ds_read_b64_tr_b16 v[70:71], v0 offset:25600
	ds_read_b64_tr_b16 v[72:73], v0 offset:26112
	s_waitcnt lgkmcnt(11)
	v_mfma_f32_32x32x16_bf16 v[82:97], v[166:169], v[134:137], v[82:97]
	v_add_f32_e32 v102, v76, v102
	v_add_f32_e32 v102, v77, v102
	v_add_f32_e32 v102, v78, v102
	v_add_f32_e32 v102, v79, v102
	v_cvt_pk_bf16_f32 v130, v74, v75
	v_cvt_pk_bf16_f32 v131, v76, v77
	ds_read_b64_tr_b16 v[74:75], v0 offset:29696
	ds_read_b64_tr_b16 v[76:77], v0 offset:30208
	s_waitcnt lgkmcnt(12)
	v_mfma_f32_32x32x16_bf16 v[34:49], v[162:165], v[134:137], v[34:49]
	v_add_f32_e32 v102, v80, v102
	v_add_f32_e32 v102, v81, v102
	v_add_f32_e32 v102, v50, v102
	v_add_f32_e32 v102, v51, v102
	v_cvt_pk_bf16_f32 v132, v78, v79
	v_cvt_pk_bf16_f32 v133, v80, v81
	ds_read_b64_tr_b16 v[78:79], v0 offset:26624
	ds_read_b64_tr_b16 v[80:81], v0 offset:27136
	s_waitcnt lgkmcnt(13)
	v_mfma_f32_32x32x16_bf16 v[82:97], v[158:161], v[126:129], v[82:97]
	v_add_f32_e32 v102, v52, v102
	v_add_f32_e32 v102, v53, v102
	v_add_f32_e32 v102, v54, v102
	v_add_f32_e32 v106, v55, v102
	v_cvt_pk_bf16_f32 v122, v50, v51
	v_cvt_pk_bf16_f32 v123, v52, v53
	ds_read_b64_tr_b16 v[102:103], v0 offset:30720
	ds_read_b64_tr_b16 v[104:105], v0 offset:31232
	s_waitcnt lgkmcnt(14)
	v_mfma_f32_32x32x16_bf16 v[34:49], v[154:157], v[126:129], v[34:49]
	v_add_f32_e32 v50, v56, v106
	v_add_f32_e32 v50, v57, v50
	v_add_f32_e32 v50, v58, v50
	v_add_f32_e32 v50, v59, v50
	v_cvt_pk_bf16_f32 v124, v54, v55
	v_cvt_pk_bf16_f32 v125, v56, v57
	ds_read_b64_tr_b16 v[106:107], v0 offset:27648
	ds_read_b64_tr_b16 v[108:109], v0 offset:28160
	s_waitcnt lgkmcnt(14)
	v_mfma_f32_32x32x16_bf16 v[82:97], v[150:153], v[118:121], v[82:97]
	v_add_f32_e32 v50, v60, v50
	v_add_f32_e32 v50, v61, v50
	v_add_f32_e32 v50, v62, v50
	v_add_f32_e32 v50, v63, v50
	v_cvt_pk_bf16_f32 v114, v58, v59
	v_cvt_pk_bf16_f32 v115, v60, v61
	ds_read_b64_tr_b16 v[110:111], v0 offset:31744
	ds_read_b64_tr_b16 v[112:113], v0 offset:32256
	v_mfma_f32_32x32x16_bf16 v[34:49], v[146:149], v[118:121], v[34:49]
	v_add_f32_e32 v0, v64, v50
	v_add_f32_e32 v0, v65, v0
	v_cvt_pk_bf16_f32 v116, v62, v63
	v_cvt_pk_bf16_f32 v117, v64, v65
	v_max_f32_e32 v50, v82, v83
	s_nop 3
	v_max3_f32 v51, v84, v85, v35
	v_max3_f32 v50, v50, v34, v36
	v_max3_f32 v50, v50, v37, v86
	v_max3_f32 v51, v51, v88, v89
	v_max3_f32 v50, v50, v87, v38
	v_max3_f32 v51, v51, v40, v41
	v_max3_f32 v50, v50, v39, v90
	v_max3_f32 v51, v51, v92, v93
	v_max3_f32 v50, v50, v91, v42
	v_max3_f32 v51, v51, v44, v45
	v_max3_f32 v50, v50, v43, v94
	v_max3_f32 v51, v51, v96, v97
	v_max3_f32 v50, v50, v95, v46
	v_max3_f32 v51, v51, v48, v49
	v_max3_f32 v50, v50, v47, v51
	v_mov_b32_e32 v51, v50
	s_nop 1
	v_permlane32_swap_b32_e32 v50, v51
	v_max_f32_e32 v50, v50, v51
	v_cmp_lt_f32_e32 vcc, s69, v50
	s_cmp_lg_u64 vcc, 0
	v_add_f32_e32 v0, v194, v0
	s_cselect_b64 s[4:5], -1, 0
	s_cbranch_vccnz .LBB0_448

.LBB0_404:
	v_add_u32_e32 v0, s36, v209
	ds_read_b64_tr_b16 v[178:179], v0 offset:24576
	ds_read_b64_tr_b16 v[180:181], v0 offset:25088
	s_waitcnt lgkmcnt(9)
	v_mfma_f32_32x32x16_bf16 v[98:113], v[174:177], v[142:145], v[34:49]
	v_add_f32_e32 v82, v66, v67
	v_add_f32_e32 v82, v68, v82
	v_add_f32_e32 v82, v69, v82
	v_add_f32_e32 v82, v70, v82
	v_add_f32_e32 v82, v71, v82
	v_cvt_pk_bf16_f32 v138, v66, v67
	v_cvt_pk_bf16_f32 v139, v68, v69
	ds_read_b64_tr_b16 v[174:175], v0 offset:28672
	ds_read_b64_tr_b16 v[176:177], v0 offset:29184
	v_add_f32_e32 v66, v72, v82
	s_waitcnt lgkmcnt(10)
	v_mfma_f32_32x32x16_bf16 v[82:97], v[170:173], v[142:145], v[34:49]
	v_add_f32_e32 v66, v73, v66
	v_add_f32_e32 v66, v74, v66
	v_add_f32_e32 v114, v75, v66
	v_cvt_pk_bf16_f32 v140, v70, v71
	v_cvt_pk_bf16_f32 v141, v72, v73
	ds_read_b64_tr_b16 v[66:67], v0 offset:25600
	ds_read_b64_tr_b16 v[68:69], v0 offset:26112
	s_waitcnt lgkmcnt(11)
	v_mfma_f32_32x32x16_bf16 v[98:113], v[166:169], v[134:137], v[98:113]
	v_add_f32_e32 v70, v76, v114
	v_add_f32_e32 v70, v77, v70
	v_add_f32_e32 v70, v78, v70
	v_add_f32_e32 v114, v79, v70
	v_cvt_pk_bf16_f32 v130, v74, v75
	v_cvt_pk_bf16_f32 v131, v76, v77
	ds_read_b64_tr_b16 v[70:71], v0 offset:29696
	ds_read_b64_tr_b16 v[72:73], v0 offset:30208
	s_waitcnt lgkmcnt(12)
	v_mfma_f32_32x32x16_bf16 v[82:97], v[162:165], v[134:137], v[82:97]
	v_add_f32_e32 v74, v80, v114
	v_add_f32_e32 v74, v81, v74
	v_add_f32_e32 v74, v50, v74
	v_add_f32_e32 v114, v51, v74
	v_cvt_pk_bf16_f32 v132, v78, v79
	v_cvt_pk_bf16_f32 v133, v80, v81
	ds_read_b64_tr_b16 v[74:75], v0 offset:26624
	ds_read_b64_tr_b16 v[76:77], v0 offset:27136
	s_waitcnt lgkmcnt(13)
	v_mfma_f32_32x32x16_bf16 v[98:113], v[158:161], v[126:129], v[98:113]
	v_add_f32_e32 v78, v52, v114
	v_add_f32_e32 v78, v53, v78
	v_add_f32_e32 v78, v54, v78
	v_add_f32_e32 v78, v55, v78
	v_cvt_pk_bf16_f32 v122, v50, v51
	v_cvt_pk_bf16_f32 v123, v52, v53
	ds_read_b64_tr_b16 v[50:51], v0 offset:30720
	ds_read_b64_tr_b16 v[52:53], v0 offset:31232
	s_waitcnt lgkmcnt(14)
	v_mfma_f32_32x32x16_bf16 v[82:97], v[154:157], v[126:129], v[82:97]
	v_add_f32_e32 v78, v56, v78
	v_add_f32_e32 v78, v57, v78
	v_add_f32_e32 v78, v58, v78
	v_add_f32_e32 v78, v59, v78
	v_cvt_pk_bf16_f32 v124, v54, v55
	v_cvt_pk_bf16_f32 v125, v56, v57
	ds_read_b64_tr_b16 v[54:55], v0 offset:27648
	ds_read_b64_tr_b16 v[56:57], v0 offset:28160
	s_waitcnt lgkmcnt(14)
	v_mfma_f32_32x32x16_bf16 v[98:113], v[150:153], v[118:121], v[98:113]
	v_add_f32_e32 v78, v60, v78
	v_add_f32_e32 v78, v61, v78
	v_add_f32_e32 v78, v62, v78
	v_add_f32_e32 v78, v63, v78
	v_cvt_pk_bf16_f32 v114, v58, v59
	v_cvt_pk_bf16_f32 v115, v60, v61
	ds_read_b64_tr_b16 v[58:59], v0 offset:31744
	ds_read_b64_tr_b16 v[60:61], v0 offset:32256
	v_mfma_f32_32x32x16_bf16 v[82:97], v[146:149], v[118:121], v[82:97]
	v_add_f32_e32 v0, v64, v78
	v_add_f32_e32 v0, v65, v0
	v_cvt_pk_bf16_f32 v116, v62, v63
	v_cvt_pk_bf16_f32 v117, v64, v65
	s_add_i32 s6, s22, 1
	s_cmp_ge_u32 s6, s28
	s_cselect_b64 s[18:19], -1, 0
	s_and_b64 vcc, exec, s[18:19]
	v_lshl_add_u64 v[196:197], v[192:193], 0, s[12:13]
	s_cbranch_vccnz .LBB0_406
	s_mov_b64 s[6:7], 0xf10c000
	v_lshl_add_u64 v[62:63], v[196:197], 0, s[6:7]
	s_add_i32 s6, s35, s29
	s_mov_b32 s7, m0
	s_mov_b32 m0, s6
	s_nop 0
	global_load_lds_dwordx4 v[62:63], off
	s_mov_b32 m0, s7
.LBB0_406:
	v_add_f32_e32 v214, v194, v0
	v_lshl_add_u64 v[194:195], v[190:191], 0, s[12:13]
	s_mov_b64 s[6:7], 0xf544000
	v_lshl_add_u64 v[62:63], v[194:195], 0, s[6:7]
	s_add_i32 s6, s37, s30
	s_mov_b32 s7, m0
	s_mov_b32 m0, s6
	s_nop 0
	global_load_lds_dwordx4 v[62:63], off
	s_mov_b32 m0, s7
	v_max_f32_e32 v0, v98, v99
	v_max3_f32 v62, v100, v101, v83
	v_max3_f32 v0, v0, v82, v84
	v_max3_f32 v0, v0, v85, v102
	v_max3_f32 v62, v62, v104, v105
	v_max3_f32 v0, v0, v103, v86
	v_max3_f32 v62, v62, v88, v89
	v_max3_f32 v0, v0, v87, v106
	v_max3_f32 v62, v62, v108, v109
	v_max3_f32 v0, v0, v107, v90
	v_max3_f32 v62, v62, v92, v93
	v_max3_f32 v0, v0, v91, v110
	v_max3_f32 v62, v62, v112, v113
	v_max3_f32 v0, v0, v111, v94
	v_max3_f32 v62, v62, v96, v97
	v_max3_f32 v0, v0, v95, v62
	v_mov_b32_e32 v62, v0
	s_nop 1
	v_permlane32_swap_b32_e32 v0, v62
	v_max_f32_e32 v0, v0, v62
	v_cmp_lt_f32_e32 vcc, s69, v0
	s_cmp_lg_u64 vcc, 0
	s_cselect_b64 s[6:7], -1, 0
	s_cbranch_vccnz .LBB0_442

.LBB0_411:
	v_add_u32_e32 v215, s35, v209
	ds_read_b64_tr_b16 v[186:187], v215 offset:24576
	ds_read_b64_tr_b16 v[188:189], v215 offset:25088
	s_waitcnt lgkmcnt(9)
	v_mfma_f32_32x32x16_bf16 v[66:81], v[174:177], v[142:145], v[34:49]
	v_add_f32_e32 v50, v98, v99
	v_add_f32_e32 v50, v100, v50
	v_add_f32_e32 v50, v101, v50
	v_add_f32_e32 v50, v102, v50
	v_add_f32_e32 v50, v103, v50
	v_cvt_pk_bf16_f32 v138, v98, v99
	v_cvt_pk_bf16_f32 v139, v100, v101
	ds_read_b64_tr_b16 v[182:183], v215 offset:28672
	ds_read_b64_tr_b16 v[184:185], v215 offset:29184
	v_add_f32_e32 v50, v104, v50
	v_add_f32_e32 v50, v105, v50
	v_add_f32_e32 v50, v106, v50
	v_add_f32_e32 v98, v107, v50
	s_waitcnt lgkmcnt(10)
	v_mfma_f32_32x32x16_bf16 v[50:65], v[170:173], v[142:145], v[34:49]
	v_cvt_pk_bf16_f32 v140, v102, v103
	v_cvt_pk_bf16_f32 v141, v104, v105
	ds_read_b64_tr_b16 v[178:179], v215 offset:25600
	ds_read_b64_tr_b16 v[180:181], v215 offset:26112
	s_waitcnt lgkmcnt(11)
	v_mfma_f32_32x32x16_bf16 v[66:81], v[166:169], v[134:137], v[66:81]
	v_add_f32_e32 v98, v108, v98
	v_add_f32_e32 v98, v109, v98
	v_add_f32_e32 v98, v110, v98
	v_add_f32_e32 v98, v111, v98
	v_cvt_pk_bf16_f32 v130, v106, v107
	v_cvt_pk_bf16_f32 v131, v108, v109
	ds_read_b64_tr_b16 v[106:107], v215 offset:29696
	ds_read_b64_tr_b16 v[108:109], v215 offset:30208
	s_waitcnt lgkmcnt(12)
	v_mfma_f32_32x32x16_bf16 v[50:65], v[162:165], v[134:137], v[50:65]
	v_add_f32_e32 v98, v112, v98
	v_add_f32_e32 v98, v113, v98
	v_add_f32_e32 v98, v82, v98
	v_add_f32_e32 v98, v83, v98
	v_cvt_pk_bf16_f32 v132, v110, v111
	v_cvt_pk_bf16_f32 v133, v112, v113
	ds_read_b64_tr_b16 v[102:103], v215 offset:26624
	ds_read_b64_tr_b16 v[104:105], v215 offset:27136
	s_waitcnt lgkmcnt(13)
	v_mfma_f32_32x32x16_bf16 v[66:81], v[158:161], v[126:129], v[66:81]
	v_add_f32_e32 v98, v84, v98
	v_add_f32_e32 v98, v85, v98
	v_add_f32_e32 v98, v86, v98
	v_add_f32_e32 v110, v87, v98
	v_cvt_pk_bf16_f32 v122, v82, v83
	v_cvt_pk_bf16_f32 v123, v84, v85
	ds_read_b64_tr_b16 v[98:99], v215 offset:30720
	ds_read_b64_tr_b16 v[100:101], v215 offset:31232
	s_waitcnt lgkmcnt(14)
	v_mfma_f32_32x32x16_bf16 v[50:65], v[154:157], v[126:129], v[50:65]
	v_add_f32_e32 v82, v88, v110
	v_add_f32_e32 v82, v89, v82
	v_add_f32_e32 v82, v90, v82
	v_add_f32_e32 v82, v91, v82
	v_cvt_pk_bf16_f32 v124, v86, v87
	v_cvt_pk_bf16_f32 v125, v88, v89
	ds_read_b64_tr_b16 v[86:87], v215 offset:27648
	ds_read_b64_tr_b16 v[88:89], v215 offset:28160
	s_waitcnt lgkmcnt(14)
	v_mfma_f32_32x32x16_bf16 v[66:81], v[150:153], v[118:121], v[66:81]
	v_add_f32_e32 v82, v92, v82
	v_add_f32_e32 v82, v93, v82
	v_add_f32_e32 v82, v94, v82
	v_add_f32_e32 v110, v95, v82
	v_cvt_pk_bf16_f32 v114, v90, v91
	v_cvt_pk_bf16_f32 v115, v92, v93
	ds_read_b64_tr_b16 v[82:83], v215 offset:31744
	ds_read_b64_tr_b16 v[84:85], v215 offset:32256
	v_mfma_f32_32x32x16_bf16 v[50:65], v[146:149], v[118:121], v[50:65]
	v_add_f32_e32 v90, v96, v110
	v_add_f32_e32 v90, v97, v90
	v_cvt_pk_bf16_f32 v116, v94, v95
	v_cvt_pk_bf16_f32 v117, v96, v97
	s_add_i32 s36, s22, 2
	s_cmp_ge_u32 s36, s28
	s_cselect_b64 s[20:21], -1, 0
	s_and_b64 vcc, exec, s[20:21]
	s_cbranch_vccnz .LBB0_413
	v_lshl_add_u64 v[92:93], v[196:197], 0, s[0:1]
	s_add_i32 s6, s37, s29
	s_mov_b32 s7, m0
	s_mov_b32 m0, s6
	s_nop 0
	global_load_lds_dwordx4 v[92:93], off
	s_mov_b32 m0, s7

.LBB0_415:
	v_add_f32_e32 v194, v214, v90
	v_max_f32_e32 v90, v66, v67
	v_max3_f32 v91, v68, v69, v51
	v_max3_f32 v90, v90, v50, v52
	v_max3_f32 v90, v90, v53, v70
	v_max3_f32 v91, v91, v72, v73
	v_max3_f32 v90, v90, v71, v54
	v_max3_f32 v91, v91, v56, v57
	v_max3_f32 v90, v90, v55, v74
	v_max3_f32 v91, v91, v76, v77
	v_max3_f32 v90, v90, v75, v58
	v_max3_f32 v91, v91, v60, v61
	v_max3_f32 v90, v90, v59, v78
	v_max3_f32 v91, v91, v80, v81
	v_max3_f32 v90, v90, v79, v62
	v_max3_f32 v91, v91, v64, v65
	v_max3_f32 v90, v90, v63, v91
	v_mov_b32_e32 v91, v90
	s_nop 1
	v_permlane32_swap_b32_e32 v90, v91
	v_max_f32_e32 v90, v90, v91
	v_cmp_lt_f32_e32 vcc, s69, v90
	s_cmp_lg_u64 vcc, 0
	s_cselect_b64 s[22:23], -1, 0
	s_cbranch_vccnz .LBB0_445
